# P2 schedule: decode-first class = 7 CUs/XCD (even grp s16<7), even s16 7..15 decode between units (small first), odd groups all decode last
# speedup vs baseline: 1.0128x; 1.0128x over previous
.LBB0_377:
	v_readlane_b32 s8, v247, 12
	s_and_b32 s1, s8, 31
	s_cmp_gt_u32 s1, 6
	s_cselect_b32 s2, 1, 0
	s_cmp_gt_u32 s1, 15
	s_cselect_b32 s3, 1, 0
	s_cmp_gt_u32 s1, 31
	s_cselect_b32 s4, 1, 0
	s_add_i32 s1, s2, s3
	s_sub_i32 s1, s1, s4
	s_and_b32 s9, s8, 15
	s_ashr_i32 s0, s8, 7
	s_cmp_lg_u32 s1, 1
	s_cselect_b64 s[2:3], -1, 0
	s_bitcmp1_b32 s8, 4
	s_cselect_b64 s[4:5], -1, 0
	v_writelane_b32 v247, s1, 37
	s_mov_b32 s1, 0xdc00000
	s_and_b64 s[6:7], s[4:5], exec
	s_cselect_b32 s1, s1, 0xcc00000
	s_or_b64 s[2:3], s[2:3], s[4:5]
	v_writelane_b32 v247, s2, 40
	s_cmpk_lt_i32 s8, 0x200
	s_mov_b32 s65, 0
	v_writelane_b32 v247, s3, 41
	s_cselect_b64 s[2:3], -1, 0
	v_writelane_b32 v247, s2, 42
	v_mov_b32_e32 v2, 0
	s_movk_i32 s79, 0x1000
	v_writelane_b32 v247, s3, 43
	v_writelane_b32 v247, s9, 44
	s_xor_b32 s2, s9, 31
	v_writelane_b32 v247, s2, 45
	s_add_u32 s2, s92, s1
	s_addc_u32 s3, s93, 0
	s_ashr_i32 s1, s0, 31
	s_lshl_b64 s[4:5], s[0:1], 13
	v_writelane_b32 v247, s4, 46
	s_mov_b32 s80, 0x41000000
	s_mov_b32 s81, 0xff800000
	v_writelane_b32 v247, s5, 47
	s_and_b32 s4, s95, 0x380
	v_readlane_b32 s5, v247, 24
	s_add_u32 s30, s5, s4
	v_readlane_b32 s5, v247, 26
	s_addc_u32 s31, s5, 0
	s_lshl_b64 s[0:1], s[0:1], 23
	s_add_u32 s5, s82, s0
	s_addc_u32 s6, s83, s1
	s_add_u32 s4, s5, s4
	s_addc_u32 s5, s6, 0
	v_writelane_b32 v247, s4, 24
	v_mov_b32_e32 v224, 0x3727c5ac
	v_mov_b32_e32 v225, 0x260
	v_writelane_b32 v247, s5, 25
	s_mov_b64 s[82:83], 0x20000
	v_readlane_b32 s4, v247, 27
	s_add_u32 s4, s4, s0
	v_readlane_b32 s5, v247, 29
	s_addc_u32 s5, s5, s1
	s_and_b32 s6, s95, 0x300
	s_add_u32 s4, s4, s6
	s_addc_u32 s5, s5, 0
	v_writelane_b32 v247, s4, 27
	s_add_u32 s34, s2, s6
	s_addc_u32 s35, s3, 0
	v_writelane_b32 v247, s5, 28
	s_and_b32 s2, s8, 0xffffffe0
	v_writelane_b32 v247, s2, 48
	s_add_u32 s2, s92, 0xc000
	v_writelane_b32 v247, s2, 49
	s_addc_u32 s2, s93, 0
	v_writelane_b32 v247, s2, 50
	s_add_u32 s2, s92, 0xbc00
	s_addc_u32 s3, s93, 0
	v_writelane_b32 v247, s2, 51
	s_mov_b64 s[76:77], 0x40000
	s_mov_b64 s[90:91], 0x5820000
	v_writelane_b32 v247, s3, 52
	s_add_u32 s2, s92, 0x4800
	s_addc_u32 s3, s93, 0
	s_or_b32 s0, s0, s6
	v_writelane_b32 v247, s2, 53
	s_add_u32 s0, s92, s0
	s_addc_u32 s1, s93, s1
	v_writelane_b32 v247, s3, 54
	v_writelane_b32 v247, s0, 29
	s_add_i32 s62, 0, 0x1a800
	s_mov_b64 s[92:93], 0x5820080
	v_writelane_b32 v247, s1, 30
	v_mov_b32_e32 v226, 1
	v_readlane_b32 s68, v247, 20
	v_readlane_b32 s69, v247, 21
	v_readlane_b32 s70, v247, 22
	v_readlane_b32 s71, v247, 23
	v_writelane_b32 v247, s30, 55
	v_writelane_b32 v247, s31, 26
	v_writelane_b32 v247, s34, 56
	v_mov_b32_e32 v227, 0xff800000
	v_mov_b32_e32 v228, 0x7f800000
	v_mov_b32_e32 v229, 0x3e4ccccd
	s_mov_b32 s88, 0
	v_writelane_b32 v247, s35, 57
	v_writelane_b32 v247, s62, 58
	s_branch .LBB0_381
